# v13 plus nt hint on the write-once f32 K/V window output stores of the in-proj epilogue
# speedup vs baseline: 1.0139x; 1.0093x over previous
; __device__ __forceinline__ v4u pack8(const f32x4 a, const f32x4 b) { v4u w; w.x = pk2(a[0], a[1]); w.y = pk2(a[2], a[3]); w.z = pk2(b[0], b[1]); w.w = pk2(b[2], b[3]); return w; }
;     __device__ __forceinline__ void operator()(const f32x4 (&acc)[2][2][4][2], const pg8::Unit& u, int wr, int wc, int fr, int fq) const {
;     ...
;             const int head = 4 * (pn & 1) + wc;
;             const bool wout = sample || (pm & 15) >= 8;
; #pragma unroll
;             for (int ai = 0; ai < 2; ++ai)
; #pragma unroll
;                 for (int m = 0; m < 4; ++m) {
;                     const int rl = 128 * ai + 64 * wr + 16 * m + tt.rr, rowa = 256 * pm + rl;
;                     const float rs = rs8[ai][m];
;                     const f32x4 a0 = acc[ai][0][m][0] * rs, a1 = acc[ai][0][m][1] * rs, b0 = acc[ai][1][m][0] * rs, b1 = acc[ai][1][m][1] * rs;
;                     { v4u a, b; tt.bf(pack8(a0, a1), pack8(b0, b1), a, b);
;                       bf16* d = (bf16*)(ws + WS_V) + (size_t)rowa * DA + head * 64 + 8 * tt.p; *(v4u*)d = a; *(v4u*)(d + 8 * DA) = b; }
;                     if (wout) {
;                         float* op = sample ? out + OUT_VNEW + (size_t)(rowa - MP) * DA : out + OUT_VWIN + ((size_t)(pm >> 4) * WIN + (256 * (pm & 15) + rl - (SEQ - WIN))) * DA;
;                         op += head * 64 + 4 * tt.p;
;                         f32x4 a, b; tt.f4(a0, a1, a, b); *(f32x4*)op = a; *(f32x4*)(op + 8 * DA) = b;
;                         tt.f4(b0, b1, a, b); *(f32x4*)(op + 32) = a; *(f32x4*)(op + 32 + 8 * DA) = b;
;                     }
.LBB0_457:
	s_andn2_b64 vcc, exec, s[6:7]
	s_cbranch_vccnz .LBB0_474
	s_lshl_b32 s0, s42, 2
	v_add_u32_e32 v153, s66, v227
	s_waitcnt vmcnt(0)
	v_pk_mul_f32 v[140:141], v[128:129], v[162:163] op_sel_hi:[1,0]
	v_pk_mul_f32 v[138:139], v[126:127], v[162:163] op_sel_hi:[1,0]
	v_pk_mul_f32 v[144:145], v[124:125], v[162:163] op_sel_hi:[1,0]
	v_pk_mul_f32 v[142:143], v[122:123], v[162:163] op_sel_hi:[1,0]
	s_and_b32 s0, s0, 4
	v_add_u32_e32 v151, s77, v229
	v_add_u32_e32 v148, s9, v153
	v_pk_mul_f32 v[132:133], v[120:121], v[162:163] op_sel_hi:[1,0]
	v_pk_mul_f32 v[130:131], v[118:119], v[162:163] op_sel_hi:[1,0]
	v_pk_mul_f32 v[136:137], v[116:117], v[162:163] op_sel_hi:[1,0]
	v_pk_mul_f32 v[134:135], v[114:115], v[162:163] op_sel_hi:[1,0]
	v_cvt_pk_bf16_f32 v154, v138, v139
	v_cvt_pk_bf16_f32 v155, v140, v141
	v_cvt_pk_bf16_f32 v156, v142, v143
	v_cvt_pk_bf16_f32 v157, v144, v145
	s_or_b32 s12, s0, s65
	s_and_b32 s0, s8, 15
	v_add_u32_e32 v152, s77, v228
	v_add_u32_e32 v150, s77, v230
	v_cvt_pk_bf16_f32 v164, v130, v131
	v_cvt_pk_bf16_f32 v165, v132, v133
	v_cvt_pk_bf16_f32 v166, v134, v135
	v_cvt_pk_bf16_f32 v167, v136, v137
	ds_write_b128 v151, v[154:157]
	ds_write_b128 v152, v[164:167]
	v_ashrrev_i32_e32 v149, 31, v148
	s_cmp_gt_u32 s0, 7
	ds_read_b128 v[154:157], v150
	ds_read_b128 v[164:167], v150 offset:1024
	v_lshlrev_b64 v[146:147], 10, v[148:149]
	s_cselect_b64 s[6:7], -1, 0
	s_lshl_b32 s1, s12, 6
	v_lshl_add_u64 v[146:147], s[26:27], 0, v[146:147]
	s_lshl_b32 s12, s12, 7
	v_lshl_add_u64 v[146:147], v[146:147], 0, s[12:13]
	v_lshlrev_b32_e32 v184, 4, v213
	v_lshl_add_u64 v[146:147], v[146:147], 0, v[184:185]
	s_waitcnt lgkmcnt(1)
	global_store_dwordx4 v[146:147], v[154:157], off
	v_add_co_u32_e32 v146, vcc, 0x2000, v146
	s_ashr_i32 s44, s8, 4
	s_nop 0
	v_addc_co_u32_e32 v147, vcc, 0, v147, vcc
	s_or_b64 s[46:47], s[4:5], s[6:7]
	s_ashr_i32 s45, s44, 31
	s_lshl_b32 s0, s0, 8
	v_lshl_or_b32 v160, v213, 2, s1
	s_waitcnt lgkmcnt(0)
	global_store_dwordx4 v[146:147], v[164:167], off
	v_cndmask_b32_e64 v146, 0, 1, s[46:47]
	s_addk_i32 s0, 0xf800
	s_lshl_b64 s[44:45], s[44:45], 22
	v_cmp_ne_u32_e64 s[6:7], 1, v146
	s_andn2_b64 vcc, exec, s[46:47]
	v_lshlrev_b32_e32 v146, 2, v160
	s_cbranch_vccnz .LBB0_460
	v_add_u32_e32 v154, s77, v226
	v_add_u32_e32 v155, s77, v225
	v_add_u32_e32 v147, s0, v153
	s_add_u32 s12, s78, s44
	v_add_u32_e32 v148, 0xffff0000, v148
	ds_write_b128 v154, v[138:141]
	ds_write_b128 v155, v[142:145]
	s_addc_u32 s33, s79, s45
	v_cndmask_b32_e64 v148, v147, v148, s[4:5]
	ds_read_b128 v[138:141], v150
	s_and_b64 s[46:47], s[4:5], exec
	v_ashrrev_i32_e32 v149, 31, v148
	s_cselect_b32 s47, s81, s33
	s_cselect_b32 s46, s80, s12
	v_lshlrev_b64 v[148:149], 11, v[148:149]
	v_lshl_add_u64 v[142:143], s[46:47], 0, v[148:149]
	v_mov_b32_e32 v147, v185
	v_lshl_add_u64 v[148:149], v[142:143], 0, v[146:147]
	ds_read_b128 v[142:145], v150 offset:1024
	s_waitcnt lgkmcnt(1)
	global_store_dwordx4 v[148:149], v[138:141], off nt
	ds_write_b128 v154, v[130:133]
	ds_write_b128 v155, v[134:137]
	ds_read_b128 v[130:133], v150
	ds_read_b128 v[134:137], v150 offset:1024
	v_add_co_u32_e32 v138, vcc, 0x4000, v148
	s_nop 1
	v_addc_co_u32_e32 v139, vcc, 0, v149, vcc
	s_waitcnt lgkmcnt(4)
	global_store_dwordx4 v[138:139], v[142:145], off nt
	s_waitcnt lgkmcnt(1)
	global_store_dwordx4 v[148:149], v[130:133], off offset:128 nt
	s_waitcnt lgkmcnt(0)
	global_store_dwordx4 v[138:139], v[134:137], off offset:128 nt
.LBB0_460:
	v_add_u32_e32 v147, 16, v153
	v_pk_mul_f32 v[140:141], v[112:113], v[210:211] op_sel_hi:[1,0]
	v_pk_mul_f32 v[138:139], v[110:111], v[210:211] op_sel_hi:[1,0]
	v_pk_mul_f32 v[144:145], v[108:109], v[210:211] op_sel_hi:[1,0]
	v_pk_mul_f32 v[142:143], v[106:107], v[210:211] op_sel_hi:[1,0]
	v_add_u32_e32 v148, s9, v147
	v_pk_mul_f32 v[132:133], v[104:105], v[210:211] op_sel_hi:[1,0]
	v_pk_mul_f32 v[130:131], v[102:103], v[210:211] op_sel_hi:[1,0]
	v_pk_mul_f32 v[136:137], v[100:101], v[210:211] op_sel_hi:[1,0]
	v_pk_mul_f32 v[134:135], v[98:99], v[210:211] op_sel_hi:[1,0]
	v_cvt_pk_bf16_f32 v154, v138, v139
	v_cvt_pk_bf16_f32 v155, v140, v141
	v_cvt_pk_bf16_f32 v156, v142, v143
	v_cvt_pk_bf16_f32 v157, v144, v145
	v_cvt_pk_bf16_f32 v164, v130, v131
	v_cvt_pk_bf16_f32 v165, v132, v133
	v_cvt_pk_bf16_f32 v166, v134, v135
	v_cvt_pk_bf16_f32 v167, v136, v137
	ds_write_b128 v151, v[154:157]
	ds_write_b128 v152, v[164:167]
	v_ashrrev_i32_e32 v149, 31, v148
	ds_read_b128 v[154:157], v150
	ds_read_b128 v[164:167], v150 offset:1024
	v_lshlrev_b64 v[160:161], 10, v[148:149]
	v_lshlrev_b32_e32 v163, 3, v213
	v_lshl_add_u64 v[160:161], s[26:27], 0, v[160:161]
	s_lshl_b32 s12, s1, 1
	v_lshl_add_u64 v[160:161], v[160:161], 0, s[12:13]
	v_lshlrev_b32_e32 v184, 1, v163
	v_lshl_add_u64 v[160:161], v[160:161], 0, v[184:185]
	s_waitcnt lgkmcnt(1)
	global_store_dwordx4 v[160:161], v[154:157], off
	s_nop 1
	v_add_co_u32_e32 v154, vcc, 0x2000, v160
	s_nop 1
	v_addc_co_u32_e32 v155, vcc, 0, v161, vcc
	s_and_b64 vcc, exec, s[6:7]
	s_waitcnt lgkmcnt(0)
	global_store_dwordx4 v[154:155], v[164:167], off
	s_cbranch_vccnz .LBB0_462
	v_add_u32_e32 v154, s77, v226
	v_add_u32_e32 v155, s77, v225
	v_add_u32_e32 v148, 0xffff0000, v148
	v_add_u32_e32 v147, s0, v147
	s_add_u32 s1, s78, s44
	ds_write_b128 v154, v[138:141]
	ds_write_b128 v155, v[142:145]
	s_addc_u32 s33, s79, s45
	v_cndmask_b32_e64 v148, v147, v148, s[4:5]
	ds_read_b128 v[138:141], v150
	s_and_b64 s[46:47], s[4:5], exec
	v_ashrrev_i32_e32 v149, 31, v148
	s_cselect_b32 s47, s81, s33
	s_cselect_b32 s46, s80, s1
	v_lshlrev_b64 v[148:149], 11, v[148:149]
	v_lshl_add_u64 v[142:143], s[46:47], 0, v[148:149]
	v_mov_b32_e32 v147, v185
	v_lshl_add_u64 v[148:149], v[142:143], 0, v[146:147]
	ds_read_b128 v[142:145], v150 offset:1024
	s_waitcnt lgkmcnt(1)
	global_store_dwordx4 v[148:149], v[138:141], off nt
	ds_write_b128 v154, v[130:133]
	ds_write_b128 v155, v[134:137]
	ds_read_b128 v[130:133], v150
	ds_read_b128 v[134:137], v150 offset:1024
	v_add_co_u32_e32 v138, vcc, 0x4000, v148
	s_nop 1
	v_addc_co_u32_e32 v139, vcc, 0, v149, vcc
	s_waitcnt lgkmcnt(4)
	global_store_dwordx4 v[138:139], v[142:145], off nt
	s_waitcnt lgkmcnt(1)
	global_store_dwordx4 v[148:149], v[130:133], off offset:128 nt
	s_waitcnt lgkmcnt(0)
	global_store_dwordx4 v[138:139], v[134:137], off offset:128 nt
; __device__ __forceinline__ v4u pack8(const f32x4 a, const f32x4 b) { v4u w; w.x = pk2(a[0], a[1]); w.y = pk2(a[2], a[3]); w.z = pk2(b[0], b[1]); w.w = pk2(b[2], b[3]); return w; }
;     __device__ __forceinline__ void operator()(const f32x4 (&acc)[2][2][4][2], const pg8::Unit& u, int wr, int wc, int fr, int fq) const {
;     ...
;             for (int ai = 0; ai < 2; ++ai)
; #pragma unroll
;                 for (int m = 0; m < 4; ++m) {
;                     const int rl = 128 * ai + 64 * wr + 16 * m + tt.rr, rowa = 256 * pm + rl;
;                     const float rs = rs8[ai][m];
;                     const f32x4 a0 = acc[ai][0][m][0] * rs, a1 = acc[ai][0][m][1] * rs, b0 = acc[ai][1][m][0] * rs, b1 = acc[ai][1][m][1] * rs;
;                     { v4u a, b; tt.bf(pack8(a0, a1), pack8(b0, b1), a, b);
;                       bf16* d = (bf16*)(ws + WS_V) + (size_t)rowa * DA + head * 64 + 8 * tt.p; *(v4u*)d = a; *(v4u*)(d + 8 * DA) = b; }
;                     if (wout) {
;                         float* op = sample ? out + OUT_VNEW + (size_t)(rowa - MP) * DA : out + OUT_VWIN + ((size_t)(pm >> 4) * WIN + (256 * (pm & 15) + rl - (SEQ - WIN))) * DA;
;                         op += head * 64 + 4 * tt.p;
;                         f32x4 a, b; tt.f4(a0, a1, a, b); *(f32x4*)op = a; *(f32x4*)(op + 8 * DA) = b;
;                         tt.f4(b0, b1, a, b); *(f32x4*)(op + 32) = a; *(f32x4*)(op + 32 + 8 * DA) = b;
;                     }
.LBB0_462:
	v_add_u32_e32 v147, 32, v153
	v_pk_mul_f32 v[140:141], v[96:97], v[208:209] op_sel_hi:[1,0]
	v_pk_mul_f32 v[138:139], v[94:95], v[208:209] op_sel_hi:[1,0]
	v_pk_mul_f32 v[144:145], v[92:93], v[208:209] op_sel_hi:[1,0]
	v_pk_mul_f32 v[142:143], v[90:91], v[208:209] op_sel_hi:[1,0]
	v_add_u32_e32 v148, s9, v147
	v_pk_mul_f32 v[132:133], v[88:89], v[208:209] op_sel_hi:[1,0]
	v_pk_mul_f32 v[130:131], v[86:87], v[208:209] op_sel_hi:[1,0]
	v_pk_mul_f32 v[136:137], v[84:85], v[208:209] op_sel_hi:[1,0]
	v_pk_mul_f32 v[134:135], v[82:83], v[208:209] op_sel_hi:[1,0]
	v_cvt_pk_bf16_f32 v154, v138, v139
	v_cvt_pk_bf16_f32 v155, v140, v141
	v_cvt_pk_bf16_f32 v156, v142, v143
	v_cvt_pk_bf16_f32 v157, v144, v145
	v_cvt_pk_bf16_f32 v164, v130, v131
	v_cvt_pk_bf16_f32 v165, v132, v133
	v_cvt_pk_bf16_f32 v166, v134, v135
	v_cvt_pk_bf16_f32 v167, v136, v137
	ds_write_b128 v151, v[154:157]
	ds_write_b128 v152, v[164:167]
	v_ashrrev_i32_e32 v149, 31, v148
	ds_read_b128 v[154:157], v150
	ds_read_b128 v[164:167], v150 offset:1024
	v_lshlrev_b64 v[160:161], 10, v[148:149]
	v_lshl_add_u64 v[160:161], s[26:27], 0, v[160:161]
	v_lshl_add_u64 v[160:161], v[160:161], 0, s[12:13]
	v_lshl_add_u64 v[160:161], v[160:161], 0, v[184:185]
	s_waitcnt lgkmcnt(1)
	global_store_dwordx4 v[160:161], v[154:157], off
	s_nop 1
	v_add_co_u32_e32 v154, vcc, 0x2000, v160
	s_nop 1
	v_addc_co_u32_e32 v155, vcc, 0, v161, vcc
	s_and_b64 vcc, exec, s[6:7]
	s_waitcnt lgkmcnt(0)
	global_store_dwordx4 v[154:155], v[164:167], off
	s_cbranch_vccnz .LBB0_464
	v_add_u32_e32 v154, s77, v226
	v_add_u32_e32 v155, s77, v225
	v_add_u32_e32 v148, 0xffff0000, v148
	v_add_u32_e32 v147, s0, v147
	s_add_u32 s1, s78, s44
	ds_write_b128 v154, v[138:141]
	ds_write_b128 v155, v[142:145]
	s_addc_u32 s33, s79, s45
	v_cndmask_b32_e64 v148, v147, v148, s[4:5]
	ds_read_b128 v[138:141], v150
	s_and_b64 s[46:47], s[4:5], exec
	v_ashrrev_i32_e32 v149, 31, v148
	s_cselect_b32 s47, s81, s33
	s_cselect_b32 s46, s80, s1
	v_lshlrev_b64 v[148:149], 11, v[148:149]
	v_lshl_add_u64 v[142:143], s[46:47], 0, v[148:149]
	v_mov_b32_e32 v147, v185
	v_lshl_add_u64 v[148:149], v[142:143], 0, v[146:147]
	ds_read_b128 v[142:145], v150 offset:1024
	s_waitcnt lgkmcnt(1)
	global_store_dwordx4 v[148:149], v[138:141], off nt
	ds_write_b128 v154, v[130:133]
	ds_write_b128 v155, v[134:137]
	ds_read_b128 v[130:133], v150
	ds_read_b128 v[134:137], v150 offset:1024
	v_add_co_u32_e32 v138, vcc, 0x4000, v148
	s_nop 1
	v_addc_co_u32_e32 v139, vcc, 0, v149, vcc
	s_waitcnt lgkmcnt(4)
	global_store_dwordx4 v[138:139], v[142:145], off nt
	s_waitcnt lgkmcnt(1)
	global_store_dwordx4 v[148:149], v[130:133], off offset:128 nt
	s_waitcnt lgkmcnt(0)
	global_store_dwordx4 v[138:139], v[134:137], off offset:128 nt
.LBB0_464:
	v_add_u32_e32 v147, 48, v153
	v_pk_mul_f32 v[140:141], v[80:81], v[206:207] op_sel_hi:[1,0]
	v_pk_mul_f32 v[138:139], v[78:79], v[206:207] op_sel_hi:[1,0]
	v_pk_mul_f32 v[144:145], v[76:77], v[206:207] op_sel_hi:[1,0]
	v_pk_mul_f32 v[142:143], v[74:75], v[206:207] op_sel_hi:[1,0]
	v_add_u32_e32 v148, s9, v147
	v_pk_mul_f32 v[132:133], v[72:73], v[206:207] op_sel_hi:[1,0]
	v_pk_mul_f32 v[130:131], v[70:71], v[206:207] op_sel_hi:[1,0]
	v_pk_mul_f32 v[136:137], v[68:69], v[206:207] op_sel_hi:[1,0]
	v_pk_mul_f32 v[134:135], v[66:67], v[206:207] op_sel_hi:[1,0]
	v_cvt_pk_bf16_f32 v154, v138, v139
	v_cvt_pk_bf16_f32 v155, v140, v141
	v_cvt_pk_bf16_f32 v156, v142, v143
	v_cvt_pk_bf16_f32 v157, v144, v145
	v_cvt_pk_bf16_f32 v164, v130, v131
	v_cvt_pk_bf16_f32 v165, v132, v133
	v_cvt_pk_bf16_f32 v166, v134, v135
	v_cvt_pk_bf16_f32 v167, v136, v137
	ds_write_b128 v151, v[154:157]
	ds_write_b128 v152, v[164:167]
	v_ashrrev_i32_e32 v149, 31, v148
	ds_read_b128 v[154:157], v150
	ds_read_b128 v[164:167], v150 offset:1024
	v_lshlrev_b64 v[160:161], 10, v[148:149]
	v_lshl_add_u64 v[160:161], s[26:27], 0, v[160:161]
	v_lshl_add_u64 v[160:161], v[160:161], 0, s[12:13]
	v_lshl_add_u64 v[160:161], v[160:161], 0, v[184:185]
	s_waitcnt lgkmcnt(1)
	global_store_dwordx4 v[160:161], v[154:157], off
	s_nop 1
	v_add_co_u32_e32 v154, vcc, 0x2000, v160
	s_nop 1
	v_addc_co_u32_e32 v155, vcc, 0, v161, vcc
	s_and_b64 vcc, exec, s[6:7]
	s_waitcnt lgkmcnt(0)
	global_store_dwordx4 v[154:155], v[164:167], off
	s_cbranch_vccnz .LBB0_466
	v_add_u32_e32 v154, s77, v226
	v_add_u32_e32 v155, s77, v225
	v_add_u32_e32 v148, 0xffff0000, v148
	v_add_u32_e32 v147, s0, v147
	s_add_u32 s1, s78, s44
	ds_write_b128 v154, v[138:141]
	ds_write_b128 v155, v[142:145]
	s_addc_u32 s33, s79, s45
	v_cndmask_b32_e64 v148, v147, v148, s[4:5]
	ds_read_b128 v[138:141], v150
	s_and_b64 s[46:47], s[4:5], exec
	v_ashrrev_i32_e32 v149, 31, v148
	s_cselect_b32 s47, s81, s33
	s_cselect_b32 s46, s80, s1
	v_lshlrev_b64 v[148:149], 11, v[148:149]
	v_lshl_add_u64 v[142:143], s[46:47], 0, v[148:149]
	v_mov_b32_e32 v147, v185
	v_lshl_add_u64 v[148:149], v[142:143], 0, v[146:147]
	ds_read_b128 v[142:145], v150 offset:1024
	s_waitcnt lgkmcnt(1)
	global_store_dwordx4 v[148:149], v[138:141], off nt
	ds_write_b128 v154, v[130:133]
	ds_write_b128 v155, v[134:137]
	ds_read_b128 v[130:133], v150
	ds_read_b128 v[134:137], v150 offset:1024
	v_add_co_u32_e32 v138, vcc, 0x4000, v148
	s_nop 1
	v_addc_co_u32_e32 v139, vcc, 0, v149, vcc
	s_waitcnt lgkmcnt(4)
	global_store_dwordx4 v[138:139], v[142:145], off nt
	s_waitcnt lgkmcnt(1)
	global_store_dwordx4 v[148:149], v[130:133], off offset:128 nt
	s_waitcnt lgkmcnt(0)
	global_store_dwordx4 v[138:139], v[134:137], off offset:128 nt
; __device__ __forceinline__ v4u pack8(const f32x4 a, const f32x4 b) { v4u w; w.x = pk2(a[0], a[1]); w.y = pk2(a[2], a[3]); w.z = pk2(b[0], b[1]); w.w = pk2(b[2], b[3]); return w; }
;     __device__ __forceinline__ void operator()(const f32x4 (&acc)[2][2][4][2], const pg8::Unit& u, int wr, int wc, int fr, int fq) const {
;     ...
;             for (int ai = 0; ai < 2; ++ai)
; #pragma unroll
;                 for (int m = 0; m < 4; ++m) {
;                     const int rl = 128 * ai + 64 * wr + 16 * m + tt.rr, rowa = 256 * pm + rl;
;                     const float rs = rs8[ai][m];
;                     const f32x4 a0 = acc[ai][0][m][0] * rs, a1 = acc[ai][0][m][1] * rs, b0 = acc[ai][1][m][0] * rs, b1 = acc[ai][1][m][1] * rs;
;                     { v4u a, b; tt.bf(pack8(a0, a1), pack8(b0, b1), a, b);
;                       bf16* d = (bf16*)(ws + WS_V) + (size_t)rowa * DA + head * 64 + 8 * tt.p; *(v4u*)d = a; *(v4u*)(d + 8 * DA) = b; }
;                     if (wout) {
;                         float* op = sample ? out + OUT_VNEW + (size_t)(rowa - MP) * DA : out + OUT_VWIN + ((size_t)(pm >> 4) * WIN + (256 * (pm & 15) + rl - (SEQ - WIN))) * DA;
;                         op += head * 64 + 4 * tt.p;
;                         f32x4 a, b; tt.f4(a0, a1, a, b); *(f32x4*)op = a; *(f32x4*)(op + 8 * DA) = b;
;                         tt.f4(b0, b1, a, b); *(f32x4*)(op + 32) = a; *(f32x4*)(op + 32 + 8 * DA) = b;
;                     }
.LBB0_466:
	v_add_u32_e32 v147, 0x80, v153
	v_pk_mul_f32 v[140:141], v[64:65], v[204:205] op_sel_hi:[1,0]
	v_pk_mul_f32 v[138:139], v[62:63], v[204:205] op_sel_hi:[1,0]
	v_pk_mul_f32 v[144:145], v[60:61], v[204:205] op_sel_hi:[1,0]
	v_pk_mul_f32 v[142:143], v[58:59], v[204:205] op_sel_hi:[1,0]
	v_add_u32_e32 v148, s9, v147
	v_pk_mul_f32 v[132:133], v[56:57], v[204:205] op_sel_hi:[1,0]
	v_pk_mul_f32 v[130:131], v[54:55], v[204:205] op_sel_hi:[1,0]
	v_pk_mul_f32 v[136:137], v[52:53], v[204:205] op_sel_hi:[1,0]
	v_pk_mul_f32 v[134:135], v[50:51], v[204:205] op_sel_hi:[1,0]
	v_cvt_pk_bf16_f32 v154, v138, v139
	v_cvt_pk_bf16_f32 v155, v140, v141
	v_cvt_pk_bf16_f32 v156, v142, v143
	v_cvt_pk_bf16_f32 v157, v144, v145
	v_cvt_pk_bf16_f32 v164, v130, v131
	v_cvt_pk_bf16_f32 v165, v132, v133
	v_cvt_pk_bf16_f32 v166, v134, v135
	v_cvt_pk_bf16_f32 v167, v136, v137
	ds_write_b128 v151, v[154:157]
	ds_write_b128 v152, v[164:167]
	v_ashrrev_i32_e32 v149, 31, v148
	ds_read_b128 v[154:157], v150
	ds_read_b128 v[164:167], v150 offset:1024
	v_lshlrev_b64 v[160:161], 10, v[148:149]
	v_lshl_add_u64 v[160:161], s[26:27], 0, v[160:161]
	v_lshl_add_u64 v[160:161], v[160:161], 0, s[12:13]
	v_lshl_add_u64 v[160:161], v[160:161], 0, v[184:185]
	s_waitcnt lgkmcnt(1)
	global_store_dwordx4 v[160:161], v[154:157], off
	s_nop 1
	v_add_co_u32_e32 v154, vcc, 0x2000, v160
	s_nop 1
	v_addc_co_u32_e32 v155, vcc, 0, v161, vcc
	s_and_b64 vcc, exec, s[6:7]
	s_waitcnt lgkmcnt(0)
	global_store_dwordx4 v[154:155], v[164:167], off
	s_cbranch_vccnz .LBB0_468
	v_add_u32_e32 v154, s77, v226
	v_add_u32_e32 v155, s77, v225
	v_add_u32_e32 v148, 0xffff0000, v148
	v_add_u32_e32 v147, s0, v147
	s_add_u32 s1, s78, s44
	ds_write_b128 v154, v[138:141]
	ds_write_b128 v155, v[142:145]
	s_addc_u32 s33, s79, s45
	v_cndmask_b32_e64 v148, v147, v148, s[4:5]
	ds_read_b128 v[138:141], v150
	s_and_b64 s[46:47], s[4:5], exec
	v_ashrrev_i32_e32 v149, 31, v148
	s_cselect_b32 s47, s81, s33
	s_cselect_b32 s46, s80, s1
	v_lshlrev_b64 v[148:149], 11, v[148:149]
	v_lshl_add_u64 v[142:143], s[46:47], 0, v[148:149]
	v_mov_b32_e32 v147, v185
	v_lshl_add_u64 v[148:149], v[142:143], 0, v[146:147]
	ds_read_b128 v[142:145], v150 offset:1024
	s_waitcnt lgkmcnt(1)
	global_store_dwordx4 v[148:149], v[138:141], off nt
	ds_write_b128 v154, v[130:133]
	ds_write_b128 v155, v[134:137]
	ds_read_b128 v[130:133], v150
	ds_read_b128 v[134:137], v150 offset:1024
	v_add_co_u32_e32 v138, vcc, 0x4000, v148
	s_nop 1
	v_addc_co_u32_e32 v139, vcc, 0, v149, vcc
	s_waitcnt lgkmcnt(4)
	global_store_dwordx4 v[138:139], v[142:145], off nt
	s_waitcnt lgkmcnt(1)
	global_store_dwordx4 v[148:149], v[130:133], off offset:128 nt
	s_waitcnt lgkmcnt(0)
	global_store_dwordx4 v[138:139], v[134:137], off offset:128 nt
.LBB0_468:
	v_add_u32_e32 v147, 0x90, v153
	v_pk_mul_f32 v[140:141], v[48:49], v[202:203] op_sel_hi:[1,0]
	v_pk_mul_f32 v[138:139], v[46:47], v[202:203] op_sel_hi:[1,0]
	v_pk_mul_f32 v[144:145], v[44:45], v[202:203] op_sel_hi:[1,0]
	v_pk_mul_f32 v[142:143], v[42:43], v[202:203] op_sel_hi:[1,0]
	v_add_u32_e32 v148, s9, v147
	v_pk_mul_f32 v[132:133], v[40:41], v[202:203] op_sel_hi:[1,0]
	v_pk_mul_f32 v[130:131], v[38:39], v[202:203] op_sel_hi:[1,0]
	v_pk_mul_f32 v[136:137], v[36:37], v[202:203] op_sel_hi:[1,0]
	v_pk_mul_f32 v[134:135], v[34:35], v[202:203] op_sel_hi:[1,0]
	v_cvt_pk_bf16_f32 v154, v138, v139
	v_cvt_pk_bf16_f32 v155, v140, v141
	v_cvt_pk_bf16_f32 v156, v142, v143
	v_cvt_pk_bf16_f32 v157, v144, v145
	v_cvt_pk_bf16_f32 v164, v130, v131
	v_cvt_pk_bf16_f32 v165, v132, v133
	v_cvt_pk_bf16_f32 v166, v134, v135
	v_cvt_pk_bf16_f32 v167, v136, v137
	ds_write_b128 v151, v[154:157]
	ds_write_b128 v152, v[164:167]
	v_ashrrev_i32_e32 v149, 31, v148
	ds_read_b128 v[154:157], v150
	ds_read_b128 v[164:167], v150 offset:1024
	v_lshlrev_b64 v[160:161], 10, v[148:149]
	v_lshl_add_u64 v[160:161], s[26:27], 0, v[160:161]
	v_lshl_add_u64 v[160:161], v[160:161], 0, s[12:13]
	v_lshl_add_u64 v[160:161], v[160:161], 0, v[184:185]
	s_waitcnt lgkmcnt(1)
	global_store_dwordx4 v[160:161], v[154:157], off
	s_nop 1
	v_add_co_u32_e32 v154, vcc, 0x2000, v160
	s_nop 1
	v_addc_co_u32_e32 v155, vcc, 0, v161, vcc
	s_and_b64 vcc, exec, s[6:7]
	s_waitcnt lgkmcnt(0)
	global_store_dwordx4 v[154:155], v[164:167], off
	s_cbranch_vccnz .LBB0_470
	v_add_u32_e32 v154, s77, v226
	v_add_u32_e32 v155, s77, v225
	v_add_u32_e32 v148, 0xffff0000, v148
	v_add_u32_e32 v147, s0, v147
	s_add_u32 s1, s78, s44
	ds_write_b128 v154, v[138:141]
	ds_write_b128 v155, v[142:145]
	s_addc_u32 s33, s79, s45
	v_cndmask_b32_e64 v148, v147, v148, s[4:5]
	ds_read_b128 v[138:141], v150
	s_and_b64 s[46:47], s[4:5], exec
	v_ashrrev_i32_e32 v149, 31, v148
	s_cselect_b32 s47, s81, s33
	s_cselect_b32 s46, s80, s1
	v_lshlrev_b64 v[148:149], 11, v[148:149]
	v_lshl_add_u64 v[142:143], s[46:47], 0, v[148:149]
	v_mov_b32_e32 v147, v185
	v_lshl_add_u64 v[148:149], v[142:143], 0, v[146:147]
	ds_read_b128 v[142:145], v150 offset:1024
	s_waitcnt lgkmcnt(1)
	global_store_dwordx4 v[148:149], v[138:141], off nt
	ds_write_b128 v154, v[130:133]
	ds_write_b128 v155, v[134:137]
	ds_read_b128 v[130:133], v150
	ds_read_b128 v[134:137], v150 offset:1024
	v_add_co_u32_e32 v138, vcc, 0x4000, v148
	s_nop 1
	v_addc_co_u32_e32 v139, vcc, 0, v149, vcc
	s_waitcnt lgkmcnt(4)
	global_store_dwordx4 v[138:139], v[142:145], off nt
	s_waitcnt lgkmcnt(1)
	global_store_dwordx4 v[148:149], v[130:133], off offset:128 nt
	s_waitcnt lgkmcnt(0)
	global_store_dwordx4 v[138:139], v[134:137], off offset:128 nt
; __device__ __forceinline__ v4u pack8(const f32x4 a, const f32x4 b) { v4u w; w.x = pk2(a[0], a[1]); w.y = pk2(a[2], a[3]); w.z = pk2(b[0], b[1]); w.w = pk2(b[2], b[3]); return w; }
;     __device__ __forceinline__ void operator()(const f32x4 (&acc)[2][2][4][2], const pg8::Unit& u, int wr, int wc, int fr, int fq) const {
;     ...
;             for (int ai = 0; ai < 2; ++ai)
; #pragma unroll
;                 for (int m = 0; m < 4; ++m) {
;                     const int rl = 128 * ai + 64 * wr + 16 * m + tt.rr, rowa = 256 * pm + rl;
;                     const float rs = rs8[ai][m];
;                     const f32x4 a0 = acc[ai][0][m][0] * rs, a1 = acc[ai][0][m][1] * rs, b0 = acc[ai][1][m][0] * rs, b1 = acc[ai][1][m][1] * rs;
;                     { v4u a, b; tt.bf(pack8(a0, a1), pack8(b0, b1), a, b);
;                       bf16* d = (bf16*)(ws + WS_V) + (size_t)rowa * DA + head * 64 + 8 * tt.p; *(v4u*)d = a; *(v4u*)(d + 8 * DA) = b; }
;                     if (wout) {
;                         float* op = sample ? out + OUT_VNEW + (size_t)(rowa - MP) * DA : out + OUT_VWIN + ((size_t)(pm >> 4) * WIN + (256 * (pm & 15) + rl - (SEQ - WIN))) * DA;
;                         op += head * 64 + 4 * tt.p;
;                         f32x4 a, b; tt.f4(a0, a1, a, b); *(f32x4*)op = a; *(f32x4*)(op + 8 * DA) = b;
;                         tt.f4(b0, b1, a, b); *(f32x4*)(op + 32) = a; *(f32x4*)(op + 32 + 8 * DA) = b;
;                     }
.LBB0_470:
	v_add_u32_e32 v147, 0xa0, v153
	v_pk_mul_f32 v[140:141], v[32:33], v[198:199] op_sel_hi:[1,0]
	v_pk_mul_f32 v[138:139], v[30:31], v[198:199] op_sel_hi:[1,0]
	v_pk_mul_f32 v[144:145], v[28:29], v[198:199] op_sel_hi:[1,0]
	v_pk_mul_f32 v[142:143], v[26:27], v[198:199] op_sel_hi:[1,0]
	v_add_u32_e32 v148, s9, v147
	v_pk_mul_f32 v[132:133], v[24:25], v[198:199] op_sel_hi:[1,0]
	v_pk_mul_f32 v[130:131], v[22:23], v[198:199] op_sel_hi:[1,0]
	v_pk_mul_f32 v[136:137], v[20:21], v[198:199] op_sel_hi:[1,0]
	v_pk_mul_f32 v[134:135], v[18:19], v[198:199] op_sel_hi:[1,0]
	v_cvt_pk_bf16_f32 v154, v138, v139
	v_cvt_pk_bf16_f32 v155, v140, v141
	v_cvt_pk_bf16_f32 v156, v142, v143
	v_cvt_pk_bf16_f32 v157, v144, v145
	v_cvt_pk_bf16_f32 v164, v130, v131
	v_cvt_pk_bf16_f32 v165, v132, v133
	v_cvt_pk_bf16_f32 v166, v134, v135
	v_cvt_pk_bf16_f32 v167, v136, v137
	ds_write_b128 v151, v[154:157]
	ds_write_b128 v152, v[164:167]
	v_ashrrev_i32_e32 v149, 31, v148
	ds_read_b128 v[154:157], v150
	ds_read_b128 v[164:167], v150 offset:1024
	v_lshlrev_b64 v[160:161], 10, v[148:149]
	v_lshl_add_u64 v[160:161], s[26:27], 0, v[160:161]
	v_lshl_add_u64 v[160:161], v[160:161], 0, s[12:13]
	v_lshl_add_u64 v[160:161], v[160:161], 0, v[184:185]
	s_waitcnt lgkmcnt(1)
	global_store_dwordx4 v[160:161], v[154:157], off
	s_nop 1
	v_add_co_u32_e32 v154, vcc, 0x2000, v160
	s_nop 1
	v_addc_co_u32_e32 v155, vcc, 0, v161, vcc
	s_and_b64 vcc, exec, s[6:7]
	s_waitcnt lgkmcnt(0)
	global_store_dwordx4 v[154:155], v[164:167], off
	s_cbranch_vccnz .LBB0_472
	v_add_u32_e32 v154, s77, v226
	v_add_u32_e32 v155, s77, v225
	v_add_u32_e32 v148, 0xffff0000, v148
	v_add_u32_e32 v147, s0, v147
	s_add_u32 s1, s78, s44
	ds_write_b128 v154, v[138:141]
	ds_write_b128 v155, v[142:145]
	s_addc_u32 s33, s79, s45
	v_cndmask_b32_e64 v148, v147, v148, s[4:5]
	ds_read_b128 v[138:141], v150
	s_and_b64 s[46:47], s[4:5], exec
	v_ashrrev_i32_e32 v149, 31, v148
	s_cselect_b32 s47, s81, s33
	s_cselect_b32 s46, s80, s1
	v_lshlrev_b64 v[148:149], 11, v[148:149]
	v_lshl_add_u64 v[142:143], s[46:47], 0, v[148:149]
	v_mov_b32_e32 v147, v185
	v_lshl_add_u64 v[148:149], v[142:143], 0, v[146:147]
	ds_read_b128 v[142:145], v150 offset:1024
	s_waitcnt lgkmcnt(1)
	global_store_dwordx4 v[148:149], v[138:141], off nt
	ds_write_b128 v154, v[130:133]
	ds_write_b128 v155, v[134:137]
	ds_read_b128 v[130:133], v150
	ds_read_b128 v[134:137], v150 offset:1024
	v_add_co_u32_e32 v138, vcc, 0x4000, v148
	s_nop 1
	v_addc_co_u32_e32 v139, vcc, 0, v149, vcc
	s_waitcnt lgkmcnt(4)
	global_store_dwordx4 v[138:139], v[142:145], off nt
	s_waitcnt lgkmcnt(1)
	global_store_dwordx4 v[148:149], v[130:133], off offset:128 nt
	s_waitcnt lgkmcnt(0)
	global_store_dwordx4 v[138:139], v[134:137], off offset:128 nt
.LBB0_472:
	v_add_u32_e32 v147, 0xb0, v153
	v_pk_mul_f32 v[140:141], v[16:17], v[196:197] op_sel_hi:[1,0]
	v_pk_mul_f32 v[138:139], v[14:15], v[196:197] op_sel_hi:[1,0]
	v_pk_mul_f32 v[144:145], v[12:13], v[196:197] op_sel_hi:[1,0]
	v_pk_mul_f32 v[142:143], v[10:11], v[196:197] op_sel_hi:[1,0]
	v_add_u32_e32 v148, s9, v147
	v_pk_mul_f32 v[132:133], v[8:9], v[196:197] op_sel_hi:[1,0]
	v_pk_mul_f32 v[130:131], v[6:7], v[196:197] op_sel_hi:[1,0]
	v_pk_mul_f32 v[136:137], v[4:5], v[196:197] op_sel_hi:[1,0]
	v_pk_mul_f32 v[134:135], v[2:3], v[196:197] op_sel_hi:[1,0]
	v_cvt_pk_bf16_f32 v154, v138, v139
	v_cvt_pk_bf16_f32 v155, v140, v141
	v_cvt_pk_bf16_f32 v156, v142, v143
	v_cvt_pk_bf16_f32 v157, v144, v145
	v_cvt_pk_bf16_f32 v164, v130, v131
	v_cvt_pk_bf16_f32 v165, v132, v133
	v_cvt_pk_bf16_f32 v166, v134, v135
	v_cvt_pk_bf16_f32 v167, v136, v137
	ds_write_b128 v151, v[154:157]
	ds_write_b128 v152, v[164:167]
	v_ashrrev_i32_e32 v149, 31, v148
	ds_read_b128 v[152:155], v150
	ds_read_b128 v[164:167], v150 offset:1024
	v_lshlrev_b64 v[156:157], 10, v[148:149]
	v_lshl_add_u64 v[156:157], s[26:27], 0, v[156:157]
	v_lshl_add_u64 v[156:157], v[156:157], 0, s[12:13]
	v_lshl_add_u64 v[156:157], v[156:157], 0, v[184:185]
	s_waitcnt lgkmcnt(1)
	global_store_dwordx4 v[156:157], v[152:155], off
	s_nop 1
	v_add_co_u32_e32 v152, vcc, 0x2000, v156
	s_nop 1
	v_addc_co_u32_e32 v153, vcc, 0, v157, vcc
	s_and_b64 vcc, exec, s[6:7]
	s_waitcnt lgkmcnt(0)
	global_store_dwordx4 v[152:153], v[164:167], off
	s_cbranch_vccnz .LBB0_474
	v_add_u32_e32 v151, s77, v226
	v_add_u32_e32 v152, s77, v225
	v_add_u32_e32 v148, 0xffff0000, v148
	v_add_u32_e32 v147, s0, v147
	s_add_u32 s6, s78, s44
	ds_write_b128 v151, v[138:141]
	ds_write_b128 v152, v[142:145]
	s_addc_u32 s7, s79, s45
	v_cndmask_b32_e64 v148, v147, v148, s[4:5]
	ds_read_b128 v[138:141], v150
	s_and_b64 s[0:1], s[4:5], exec
	v_ashrrev_i32_e32 v149, 31, v148
	s_cselect_b32 s1, s81, s7
	s_cselect_b32 s0, s80, s6
	v_lshlrev_b64 v[148:149], 11, v[148:149]
	v_lshl_add_u64 v[142:143], s[0:1], 0, v[148:149]
	v_mov_b32_e32 v147, v185
	v_lshl_add_u64 v[146:147], v[142:143], 0, v[146:147]
	ds_read_b128 v[142:145], v150 offset:1024
	s_waitcnt lgkmcnt(1)
	global_store_dwordx4 v[146:147], v[138:141], off nt
	ds_write_b128 v151, v[130:133]
	ds_write_b128 v152, v[134:137]
	ds_read_b128 v[130:133], v150
	ds_read_b128 v[134:137], v150 offset:1024
	v_add_co_u32_e32 v138, vcc, 0x4000, v146
	s_nop 1
	v_addc_co_u32_e32 v139, vcc, 0, v147, vcc
	s_waitcnt lgkmcnt(4)
	global_store_dwordx4 v[138:139], v[142:145], off nt
	s_waitcnt lgkmcnt(1)
	global_store_dwordx4 v[146:147], v[130:133], off offset:128 nt
	s_waitcnt lgkmcnt(0)
	global_store_dwordx4 v[138:139], v[134:137], off offset:128 nt

; __device__ __forceinline__ v4u pack8(const f32x4 a, const f32x4 b) { v4u w; w.x = pk2(a[0], a[1]); w.y = pk2(a[2], a[3]); w.z = pk2(b[0], b[1]); w.w = pk2(b[2], b[3]); return w; }
;     __device__ __forceinline__ void operator()(const f32x4 (&acc)[2][2][4][2], const pg8::Unit& u, int wr, int wc, int fr, int fq) const {
;     ...
;                     const int rowa = 256 * pm + 128 * ai + 64 * wr + 16 * m + tt.rr;
;                     { v4u a, b; if (isq) tt.bf(pack8(o1[0] * QSCALE, o1[1] * QSCALE), pack8(o2[0] * QSCALE, o2[1] * QSCALE), a, b); else tt.bf(pack8(o1[0], o1[1]), pack8(o2[0], o2[1]), a, b);
;                       bf16* d = dst + (size_t)rowa * DA + head * 64 + 8 * tt.p; *(v4u*)d = a; *(v4u*)(d + 8 * DA) = b; }
;                     if (wout) {
;                         const int rl = 128 * ai + 64 * wr + 16 * m + tt.rr;
;                         float* op = sample ? out + OUT_KNEW + (size_t)(rowa - MP) * DA : out + OUT_KWIN + ((size_t)(pm >> 4) * WIN + (256 * (pm & 15) + rl - (SEQ - WIN))) * DA;
;                         op += head * 64 + 4 * tt.p;
;                         f32x4 a, b; tt.f4(o1[0], o1[1], a, b); *(f32x4*)op = a; *(f32x4*)(op + 8 * DA) = b;
;                         tt.f4(o2[0], o2[1], a, b); *(f32x4*)(op + 32) = a; *(f32x4*)(op + 32 + 8 * DA) = b;
.LBB0_480:
	s_lshl_b32 s1, s42, 2
	s_and_b32 s1, s1, 4
	s_and_b64 s[6:7], s[46:47], exec
	s_cselect_b32 s12, s93, 0xa000000
	s_bitcmp1_b32 s8, 3
	s_cselect_b64 s[6:7], -1, 0
	s_or_b64 s[6:7], s[4:5], s[6:7]
	s_or_b32 s1, s1, s65
	s_add_u32 s12, s58, s12
	s_addc_u32 s33, s59, 0
	s_add_i32 s9, s9, s66
	v_cvt_pk_bf16_f32 v232, v166, v167
	v_add_u32_e32 v166, s77, v229
	s_and_b64 s[46:47], s[46:47], s[6:7]
	v_add_u32_e32 v212, s9, v227
	s_lshl_b32 s9, s1, 6
	s_lshl_b32 s1, s1, 7
	v_cvt_pk_bf16_f32 v233, v168, v169
	v_cvt_pk_bf16_f32 v234, v170, v171
	v_cvt_pk_bf16_f32 v235, v172, v173
	ds_write_b128 v166, v[162:165]
	v_add_u32_e32 v165, s77, v228
	s_add_u32 s6, s12, s1
	ds_write_b128 v165, v[232:235]
	v_add_u32_e32 v162, s77, v230
	s_addc_u32 s7, s33, 0
	v_lshlrev_b32_e32 v184, 4, v213
	ds_read_b128 v[168:171], v162
	ds_read_b128 v[228:231], v162 offset:1024
	v_lshl_add_u64 v[214:215], s[6:7], 0, v[184:185]
	v_lshl_or_b32 v184, v213, 2, s9
	v_ashrrev_i32_e32 v213, 31, v212
	v_lshlrev_b64 v[172:173], 10, v[212:213]
	v_lshl_add_u64 v[172:173], v[214:215], 0, v[172:173]
	s_ashr_i32 s6, s8, 4
	s_waitcnt lgkmcnt(1)
	global_store_dwordx4 v[172:173], v[168:171], off
	s_ashr_i32 s7, s6, 31
	s_add_i32 s0, s70, s0
	v_add_co_u32_e32 v168, vcc, 0x2000, v172
	v_cndmask_b32_e64 v163, 0, 1, s[46:47]
	s_nop 0
	v_addc_co_u32_e32 v169, vcc, 0, v173, vcc
	v_add_u32_e32 v199, s0, v227
	s_lshl_b64 s[42:43], s[6:7], 22
	v_cmp_ne_u32_e64 s[6:7], 1, v163
	s_andn2_b64 vcc, exec, s[46:47]
	v_add_u32_e32 v163, s77, v226
	v_add_u32_e32 v164, s77, v225
	v_lshlrev_b32_e32 v184, 2, v184
	s_waitcnt lgkmcnt(0)
	global_store_dwordx4 v[168:169], v[228:231], off
	s_cbranch_vccnz .LBB0_482
	s_add_u32 s8, s82, s42
	v_add_u32_e32 v167, 0xffff0000, v212
	ds_write_b128 v163, v[118:121]
	ds_write_b128 v164, v[126:129]
	s_addc_u32 s9, s83, s43
	v_cndmask_b32_e64 v168, v199, v167, s[4:5]
	ds_read_b128 v[118:121], v162
	s_and_b64 s[0:1], s[4:5], exec
	v_ashrrev_i32_e32 v169, 31, v168
	s_cselect_b32 s1, s85, s9
	s_cselect_b32 s0, s84, s8
	v_lshlrev_b64 v[126:127], 11, v[168:169]
	v_lshl_add_u64 v[126:127], s[0:1], 0, v[126:127]
	v_lshl_add_u64 v[168:169], v[126:127], 0, v[184:185]
	ds_read_b128 v[126:129], v162 offset:1024
	s_waitcnt lgkmcnt(1)
	global_store_dwordx4 v[168:169], v[118:121], off nt
	ds_write_b128 v163, v[114:117]
	ds_write_b128 v164, v[122:125]
	ds_read_b128 v[114:117], v162
	ds_read_b128 v[118:121], v162 offset:1024
	v_add_co_u32_e32 v170, vcc, 0x4000, v168
	s_nop 1
	v_addc_co_u32_e32 v171, vcc, 0, v169, vcc
	s_waitcnt lgkmcnt(4)
	global_store_dwordx4 v[170:171], v[126:129], off nt
	s_waitcnt lgkmcnt(1)
	global_store_dwordx4 v[168:169], v[114:117], off offset:128 nt
	s_waitcnt lgkmcnt(0)
	global_store_dwordx4 v[170:171], v[118:121], off offset:128 nt

; __device__ __forceinline__ v4u pack8(const f32x4 a, const f32x4 b) { v4u w; w.x = pk2(a[0], a[1]); w.y = pk2(a[2], a[3]); w.z = pk2(b[0], b[1]); w.w = pk2(b[2], b[3]); return w; }
;     __device__ __forceinline__ void operator()(const f32x4 (&acc)[2][2][4][2], const pg8::Unit& u, int wr, int wc, int fr, int fq) const {
;     ...
;                     const int rowa = 256 * pm + 128 * ai + 64 * wr + 16 * m + tt.rr;
;                     { v4u a, b; if (isq) tt.bf(pack8(o1[0] * QSCALE, o1[1] * QSCALE), pack8(o2[0] * QSCALE, o2[1] * QSCALE), a, b); else tt.bf(pack8(o1[0], o1[1]), pack8(o2[0], o2[1]), a, b);
;                       bf16* d = dst + (size_t)rowa * DA + head * 64 + 8 * tt.p; *(v4u*)d = a; *(v4u*)(d + 8 * DA) = b; }
;                     if (wout) {
;                         const int rl = 128 * ai + 64 * wr + 16 * m + tt.rr;
;                         float* op = sample ? out + OUT_KNEW + (size_t)(rowa - MP) * DA : out + OUT_KWIN + ((size_t)(pm >> 4) * WIN + (256 * (pm & 15) + rl - (SEQ - WIN))) * DA;
;                         op += head * 64 + 4 * tt.p;
;                         f32x4 a, b; tt.f4(o1[0], o1[1], a, b); *(f32x4*)op = a; *(f32x4*)(op + 8 * DA) = b;
;                         tt.f4(o2[0], o2[1], a, b); *(f32x4*)(op + 32) = a; *(f32x4*)(op + 32 + 8 * DA) = b;
.LBB0_486:
	v_cvt_pk_bf16_f32 v150, v150, v151
	v_cvt_pk_bf16_f32 v151, v152, v153
	v_cvt_pk_bf16_f32 v152, v154, v155
	v_cvt_pk_bf16_f32 v153, v156, v157
	ds_write_b128 v166, v[146:149]
	ds_write_b128 v165, v[150:153]
	v_add_u32_e32 v158, 16, v212
	ds_read_b128 v[146:149], v162
	ds_read_b128 v[150:153], v162 offset:1024
	v_ashrrev_i32_e32 v159, 31, v158
	v_lshlrev_b64 v[154:155], 10, v[158:159]
	v_lshl_add_u64 v[154:155], v[214:215], 0, v[154:155]
	s_waitcnt lgkmcnt(1)
	global_store_dwordx4 v[154:155], v[146:149], off
	s_nop 1
	v_add_co_u32_e32 v146, vcc, 0x2000, v154
	s_nop 1
	v_addc_co_u32_e32 v147, vcc, 0, v155, vcc
	s_and_b64 vcc, exec, s[6:7]
	s_waitcnt lgkmcnt(0)
	global_store_dwordx4 v[146:147], v[150:153], off
	s_cbranch_vccnz .LBB0_488
	v_add_u32_e32 v146, 0xffff0010, v212
	v_add_u32_e32 v147, 16, v199
	s_add_u32 s12, s82, s42
	ds_write_b128 v163, v[102:105]
	ds_write_b128 v164, v[110:113]
	s_addc_u32 s33, s83, s43
	v_cndmask_b32_e64 v146, v147, v146, s[4:5]
	ds_read_b128 v[102:105], v162
	s_and_b64 s[0:1], s[4:5], exec
	v_ashrrev_i32_e32 v147, 31, v146
	s_cselect_b32 s1, s85, s33
	s_cselect_b32 s0, s84, s12
	v_lshlrev_b64 v[110:111], 11, v[146:147]
	v_lshl_add_u64 v[110:111], s[0:1], 0, v[110:111]
	v_lshl_add_u64 v[146:147], v[110:111], 0, v[184:185]
	ds_read_b128 v[110:113], v162 offset:1024
	s_waitcnt lgkmcnt(1)
	global_store_dwordx4 v[146:147], v[102:105], off nt
	ds_write_b128 v163, v[98:101]
	ds_write_b128 v164, v[106:109]
	ds_read_b128 v[98:101], v162
	ds_read_b128 v[102:105], v162 offset:1024
	v_add_co_u32_e32 v148, vcc, 0x4000, v146
	s_nop 1
	v_addc_co_u32_e32 v149, vcc, 0, v147, vcc
	s_waitcnt lgkmcnt(4)
	global_store_dwordx4 v[148:149], v[110:113], off nt
	s_waitcnt lgkmcnt(1)
	global_store_dwordx4 v[146:147], v[98:101], off offset:128 nt
	s_waitcnt lgkmcnt(0)
	global_store_dwordx4 v[148:149], v[102:105], off offset:128 nt

; __device__ __forceinline__ v4u pack8(const f32x4 a, const f32x4 b) { v4u w; w.x = pk2(a[0], a[1]); w.y = pk2(a[2], a[3]); w.z = pk2(b[0], b[1]); w.w = pk2(b[2], b[3]); return w; }
;     __device__ __forceinline__ void operator()(const f32x4 (&acc)[2][2][4][2], const pg8::Unit& u, int wr, int wc, int fr, int fq) const {
;     ...
;                     const int rowa = 256 * pm + 128 * ai + 64 * wr + 16 * m + tt.rr;
;                     { v4u a, b; if (isq) tt.bf(pack8(o1[0] * QSCALE, o1[1] * QSCALE), pack8(o2[0] * QSCALE, o2[1] * QSCALE), a, b); else tt.bf(pack8(o1[0], o1[1]), pack8(o2[0], o2[1]), a, b);
;                       bf16* d = dst + (size_t)rowa * DA + head * 64 + 8 * tt.p; *(v4u*)d = a; *(v4u*)(d + 8 * DA) = b; }
;                     if (wout) {
;                         const int rl = 128 * ai + 64 * wr + 16 * m + tt.rr;
;                         float* op = sample ? out + OUT_KNEW + (size_t)(rowa - MP) * DA : out + OUT_KWIN + ((size_t)(pm >> 4) * WIN + (256 * (pm & 15) + rl - (SEQ - WIN))) * DA;
;                         op += head * 64 + 4 * tt.p;
;                         f32x4 a, b; tt.f4(o1[0], o1[1], a, b); *(f32x4*)op = a; *(f32x4*)(op + 8 * DA) = b;
;                         tt.f4(o2[0], o2[1], a, b); *(f32x4*)(op + 32) = a; *(f32x4*)(op + 32 + 8 * DA) = b;
.LBB0_492:
	v_cvt_pk_bf16_f32 v118, v118, v119
	v_cvt_pk_bf16_f32 v119, v120, v121
	v_cvt_pk_bf16_f32 v120, v122, v123
	v_cvt_pk_bf16_f32 v121, v124, v125
	ds_write_b128 v166, v[114:117]
	ds_write_b128 v165, v[118:121]
	v_add_u32_e32 v126, 32, v212
	ds_read_b128 v[114:117], v162
	ds_read_b128 v[118:121], v162 offset:1024
	v_ashrrev_i32_e32 v127, 31, v126
	v_lshlrev_b64 v[122:123], 10, v[126:127]
	v_lshl_add_u64 v[122:123], v[214:215], 0, v[122:123]
	s_waitcnt lgkmcnt(1)
	global_store_dwordx4 v[122:123], v[114:117], off
	s_nop 1
	v_add_co_u32_e32 v114, vcc, 0x2000, v122
	s_nop 1
	v_addc_co_u32_e32 v115, vcc, 0, v123, vcc
	s_and_b64 vcc, exec, s[6:7]
	s_waitcnt lgkmcnt(0)
	global_store_dwordx4 v[114:115], v[118:121], off
	s_cbranch_vccnz .LBB0_494
	v_add_u32_e32 v114, 0xffff0020, v212
	v_add_u32_e32 v115, 32, v199
	s_add_u32 s12, s82, s42
	ds_write_b128 v163, v[86:89]
	ds_write_b128 v164, v[94:97]
	s_addc_u32 s33, s83, s43
	v_cndmask_b32_e64 v114, v115, v114, s[4:5]
	ds_read_b128 v[86:89], v162
	s_and_b64 s[0:1], s[4:5], exec
	v_ashrrev_i32_e32 v115, 31, v114
	s_cselect_b32 s1, s85, s33
	s_cselect_b32 s0, s84, s12
	v_lshlrev_b64 v[94:95], 11, v[114:115]
	v_lshl_add_u64 v[94:95], s[0:1], 0, v[94:95]
	v_lshl_add_u64 v[114:115], v[94:95], 0, v[184:185]
	ds_read_b128 v[94:97], v162 offset:1024
	s_waitcnt lgkmcnt(1)
	global_store_dwordx4 v[114:115], v[86:89], off nt
	ds_write_b128 v163, v[82:85]
	ds_write_b128 v164, v[90:93]
	ds_read_b128 v[82:85], v162
	ds_read_b128 v[86:89], v162 offset:1024
	v_add_co_u32_e32 v116, vcc, 0x4000, v114
	s_nop 1
	v_addc_co_u32_e32 v117, vcc, 0, v115, vcc
	s_waitcnt lgkmcnt(4)
	global_store_dwordx4 v[116:117], v[94:97], off nt
	s_waitcnt lgkmcnt(1)
	global_store_dwordx4 v[114:115], v[82:85], off offset:128 nt
	s_waitcnt lgkmcnt(0)
	global_store_dwordx4 v[116:117], v[86:89], off offset:128 nt

; __device__ __forceinline__ v4u pack8(const f32x4 a, const f32x4 b) { v4u w; w.x = pk2(a[0], a[1]); w.y = pk2(a[2], a[3]); w.z = pk2(b[0], b[1]); w.w = pk2(b[2], b[3]); return w; }
;     __device__ __forceinline__ void operator()(const f32x4 (&acc)[2][2][4][2], const pg8::Unit& u, int wr, int wc, int fr, int fq) const {
;     ...
;                     const int rowa = 256 * pm + 128 * ai + 64 * wr + 16 * m + tt.rr;
;                     { v4u a, b; if (isq) tt.bf(pack8(o1[0] * QSCALE, o1[1] * QSCALE), pack8(o2[0] * QSCALE, o2[1] * QSCALE), a, b); else tt.bf(pack8(o1[0], o1[1]), pack8(o2[0], o2[1]), a, b);
;                       bf16* d = dst + (size_t)rowa * DA + head * 64 + 8 * tt.p; *(v4u*)d = a; *(v4u*)(d + 8 * DA) = b; }
;                     if (wout) {
;                         const int rl = 128 * ai + 64 * wr + 16 * m + tt.rr;
;                         float* op = sample ? out + OUT_KNEW + (size_t)(rowa - MP) * DA : out + OUT_KWIN + ((size_t)(pm >> 4) * WIN + (256 * (pm & 15) + rl - (SEQ - WIN))) * DA;
;                         op += head * 64 + 4 * tt.p;
;                         f32x4 a, b; tt.f4(o1[0], o1[1], a, b); *(f32x4*)op = a; *(f32x4*)(op + 8 * DA) = b;
;                         tt.f4(o2[0], o2[1], a, b); *(f32x4*)(op + 32) = a; *(f32x4*)(op + 32 + 8 * DA) = b;
.LBB0_498:
	v_cvt_pk_bf16_f32 v102, v102, v103
	v_cvt_pk_bf16_f32 v103, v104, v105
	v_cvt_pk_bf16_f32 v104, v106, v107
	v_cvt_pk_bf16_f32 v105, v108, v109
	ds_write_b128 v166, v[98:101]
	ds_write_b128 v165, v[102:105]
	v_add_u32_e32 v110, 48, v212
	ds_read_b128 v[98:101], v162
	ds_read_b128 v[102:105], v162 offset:1024
	v_ashrrev_i32_e32 v111, 31, v110
	v_lshlrev_b64 v[106:107], 10, v[110:111]
	v_lshl_add_u64 v[106:107], v[214:215], 0, v[106:107]
	s_waitcnt lgkmcnt(1)
	global_store_dwordx4 v[106:107], v[98:101], off
	s_nop 1
	v_add_co_u32_e32 v98, vcc, 0x2000, v106
	s_nop 1
	v_addc_co_u32_e32 v99, vcc, 0, v107, vcc
	s_and_b64 vcc, exec, s[6:7]
	s_waitcnt lgkmcnt(0)
	global_store_dwordx4 v[98:99], v[102:105], off
	s_cbranch_vccnz .LBB0_500
	v_add_u32_e32 v98, 0xffff0030, v212
	v_add_u32_e32 v99, 48, v199
	s_add_u32 s12, s82, s42
	ds_write_b128 v163, v[70:73]
	ds_write_b128 v164, v[78:81]
	s_addc_u32 s33, s83, s43
	v_cndmask_b32_e64 v98, v99, v98, s[4:5]
	ds_read_b128 v[70:73], v162
	s_and_b64 s[0:1], s[4:5], exec
	v_ashrrev_i32_e32 v99, 31, v98
	s_cselect_b32 s1, s85, s33
	s_cselect_b32 s0, s84, s12
	v_lshlrev_b64 v[78:79], 11, v[98:99]
	v_lshl_add_u64 v[78:79], s[0:1], 0, v[78:79]
	v_lshl_add_u64 v[98:99], v[78:79], 0, v[184:185]
	ds_read_b128 v[78:81], v162 offset:1024
	s_waitcnt lgkmcnt(1)
	global_store_dwordx4 v[98:99], v[70:73], off nt
	ds_write_b128 v163, v[66:69]
	ds_write_b128 v164, v[74:77]
	ds_read_b128 v[66:69], v162
	ds_read_b128 v[70:73], v162 offset:1024
	v_add_co_u32_e32 v100, vcc, 0x4000, v98
	s_nop 1
	v_addc_co_u32_e32 v101, vcc, 0, v99, vcc
	s_waitcnt lgkmcnt(4)
	global_store_dwordx4 v[100:101], v[78:81], off nt
	s_waitcnt lgkmcnt(1)
	global_store_dwordx4 v[98:99], v[66:69], off offset:128 nt
	s_waitcnt lgkmcnt(0)
	global_store_dwordx4 v[100:101], v[70:73], off offset:128 nt

; __device__ __forceinline__ v4u pack8(const f32x4 a, const f32x4 b) { v4u w; w.x = pk2(a[0], a[1]); w.y = pk2(a[2], a[3]); w.z = pk2(b[0], b[1]); w.w = pk2(b[2], b[3]); return w; }
;     __device__ __forceinline__ void operator()(const f32x4 (&acc)[2][2][4][2], const pg8::Unit& u, int wr, int wc, int fr, int fq) const {
;     ...
;                     const int rowa = 256 * pm + 128 * ai + 64 * wr + 16 * m + tt.rr;
;                     { v4u a, b; if (isq) tt.bf(pack8(o1[0] * QSCALE, o1[1] * QSCALE), pack8(o2[0] * QSCALE, o2[1] * QSCALE), a, b); else tt.bf(pack8(o1[0], o1[1]), pack8(o2[0], o2[1]), a, b);
;                       bf16* d = dst + (size_t)rowa * DA + head * 64 + 8 * tt.p; *(v4u*)d = a; *(v4u*)(d + 8 * DA) = b; }
;                     if (wout) {
;                         const int rl = 128 * ai + 64 * wr + 16 * m + tt.rr;
;                         float* op = sample ? out + OUT_KNEW + (size_t)(rowa - MP) * DA : out + OUT_KWIN + ((size_t)(pm >> 4) * WIN + (256 * (pm & 15) + rl - (SEQ - WIN))) * DA;
;                         op += head * 64 + 4 * tt.p;
;                         f32x4 a, b; tt.f4(o1[0], o1[1], a, b); *(f32x4*)op = a; *(f32x4*)(op + 8 * DA) = b;
;                         tt.f4(o2[0], o2[1], a, b); *(f32x4*)(op + 32) = a; *(f32x4*)(op + 32 + 8 * DA) = b;
.LBB0_504:
	v_cvt_pk_bf16_f32 v86, v86, v87
	v_cvt_pk_bf16_f32 v87, v88, v89
	v_cvt_pk_bf16_f32 v88, v90, v91
	v_cvt_pk_bf16_f32 v89, v92, v93
	ds_write_b128 v166, v[82:85]
	ds_write_b128 v165, v[86:89]
	v_add_u32_e32 v94, 0x80, v212
	ds_read_b128 v[82:85], v162
	ds_read_b128 v[86:89], v162 offset:1024
	v_ashrrev_i32_e32 v95, 31, v94
	v_lshlrev_b64 v[90:91], 10, v[94:95]
	v_lshl_add_u64 v[90:91], v[214:215], 0, v[90:91]
	s_waitcnt lgkmcnt(1)
	global_store_dwordx4 v[90:91], v[82:85], off
	s_nop 1
	v_add_co_u32_e32 v82, vcc, 0x2000, v90
	s_nop 1
	v_addc_co_u32_e32 v83, vcc, 0, v91, vcc
	s_and_b64 vcc, exec, s[6:7]
	s_waitcnt lgkmcnt(0)
	global_store_dwordx4 v[82:83], v[86:89], off
	s_cbranch_vccnz .LBB0_506
	v_add_u32_e32 v82, 0x80, v199
	v_add_u32_e32 v83, 0xffff0080, v212
	s_add_u32 s12, s82, s42
	ds_write_b128 v163, v[54:57]
	ds_write_b128 v164, v[62:65]
	s_addc_u32 s33, s83, s43
	v_cndmask_b32_e64 v82, v82, v83, s[4:5]
	ds_read_b128 v[54:57], v162
	s_and_b64 s[0:1], s[4:5], exec
	v_ashrrev_i32_e32 v83, 31, v82
	s_cselect_b32 s1, s85, s33
	s_cselect_b32 s0, s84, s12
	v_lshlrev_b64 v[62:63], 11, v[82:83]
	v_lshl_add_u64 v[62:63], s[0:1], 0, v[62:63]
	v_lshl_add_u64 v[82:83], v[62:63], 0, v[184:185]
	ds_read_b128 v[62:65], v162 offset:1024
	s_waitcnt lgkmcnt(1)
	global_store_dwordx4 v[82:83], v[54:57], off nt
	ds_write_b128 v163, v[50:53]
	ds_write_b128 v164, v[58:61]
	ds_read_b128 v[50:53], v162
	ds_read_b128 v[54:57], v162 offset:1024
	v_add_co_u32_e32 v84, vcc, 0x4000, v82
	s_nop 1
	v_addc_co_u32_e32 v85, vcc, 0, v83, vcc
	s_waitcnt lgkmcnt(4)
	global_store_dwordx4 v[84:85], v[62:65], off nt
	s_waitcnt lgkmcnt(1)
	global_store_dwordx4 v[82:83], v[50:53], off offset:128 nt
	s_waitcnt lgkmcnt(0)
	global_store_dwordx4 v[84:85], v[54:57], off offset:128 nt

; __device__ __forceinline__ v4u pack8(const f32x4 a, const f32x4 b) { v4u w; w.x = pk2(a[0], a[1]); w.y = pk2(a[2], a[3]); w.z = pk2(b[0], b[1]); w.w = pk2(b[2], b[3]); return w; }
;     __device__ __forceinline__ void operator()(const f32x4 (&acc)[2][2][4][2], const pg8::Unit& u, int wr, int wc, int fr, int fq) const {
;     ...
;                     const int rowa = 256 * pm + 128 * ai + 64 * wr + 16 * m + tt.rr;
;                     { v4u a, b; if (isq) tt.bf(pack8(o1[0] * QSCALE, o1[1] * QSCALE), pack8(o2[0] * QSCALE, o2[1] * QSCALE), a, b); else tt.bf(pack8(o1[0], o1[1]), pack8(o2[0], o2[1]), a, b);
;                       bf16* d = dst + (size_t)rowa * DA + head * 64 + 8 * tt.p; *(v4u*)d = a; *(v4u*)(d + 8 * DA) = b; }
;                     if (wout) {
;                         const int rl = 128 * ai + 64 * wr + 16 * m + tt.rr;
;                         float* op = sample ? out + OUT_KNEW + (size_t)(rowa - MP) * DA : out + OUT_KWIN + ((size_t)(pm >> 4) * WIN + (256 * (pm & 15) + rl - (SEQ - WIN))) * DA;
;                         op += head * 64 + 4 * tt.p;
;                         f32x4 a, b; tt.f4(o1[0], o1[1], a, b); *(f32x4*)op = a; *(f32x4*)(op + 8 * DA) = b;
;                         tt.f4(o2[0], o2[1], a, b); *(f32x4*)(op + 32) = a; *(f32x4*)(op + 32 + 8 * DA) = b;
.LBB0_510:
	v_cvt_pk_bf16_f32 v70, v70, v71
	v_cvt_pk_bf16_f32 v71, v72, v73
	v_cvt_pk_bf16_f32 v72, v74, v75
	v_cvt_pk_bf16_f32 v73, v76, v77
	ds_write_b128 v166, v[66:69]
	ds_write_b128 v165, v[70:73]
	v_add_u32_e32 v78, 0x90, v212
	ds_read_b128 v[66:69], v162
	ds_read_b128 v[70:73], v162 offset:1024
	v_ashrrev_i32_e32 v79, 31, v78
	v_lshlrev_b64 v[74:75], 10, v[78:79]
	v_lshl_add_u64 v[74:75], v[214:215], 0, v[74:75]
	s_waitcnt lgkmcnt(1)
	global_store_dwordx4 v[74:75], v[66:69], off
	s_nop 1
	v_add_co_u32_e32 v66, vcc, 0x2000, v74
	s_nop 1
	v_addc_co_u32_e32 v67, vcc, 0, v75, vcc
	s_and_b64 vcc, exec, s[6:7]
	s_waitcnt lgkmcnt(0)
	global_store_dwordx4 v[66:67], v[70:73], off
	s_cbranch_vccnz .LBB0_512
	v_add_u32_e32 v66, 0xffff0090, v212
	v_add_u32_e32 v67, 0x90, v199
	s_add_u32 s12, s82, s42
	ds_write_b128 v163, v[38:41]
	ds_write_b128 v164, v[46:49]
	s_addc_u32 s33, s83, s43
	v_cndmask_b32_e64 v66, v67, v66, s[4:5]
	ds_read_b128 v[38:41], v162
	s_and_b64 s[0:1], s[4:5], exec
	v_ashrrev_i32_e32 v67, 31, v66
	s_cselect_b32 s1, s85, s33
	s_cselect_b32 s0, s84, s12
	v_lshlrev_b64 v[46:47], 11, v[66:67]
	v_lshl_add_u64 v[46:47], s[0:1], 0, v[46:47]
	v_lshl_add_u64 v[66:67], v[46:47], 0, v[184:185]
	ds_read_b128 v[46:49], v162 offset:1024
	s_waitcnt lgkmcnt(1)
	global_store_dwordx4 v[66:67], v[38:41], off nt
	ds_write_b128 v163, v[34:37]
	ds_write_b128 v164, v[42:45]
	ds_read_b128 v[34:37], v162
	ds_read_b128 v[38:41], v162 offset:1024
	v_add_co_u32_e32 v68, vcc, 0x4000, v66
	s_nop 1
	v_addc_co_u32_e32 v69, vcc, 0, v67, vcc
	s_waitcnt lgkmcnt(4)
	global_store_dwordx4 v[68:69], v[46:49], off nt
	s_waitcnt lgkmcnt(1)
	global_store_dwordx4 v[66:67], v[34:37], off offset:128 nt
	s_waitcnt lgkmcnt(0)
	global_store_dwordx4 v[68:69], v[38:41], off offset:128 nt

; __device__ __forceinline__ v4u pack8(const f32x4 a, const f32x4 b) { v4u w; w.x = pk2(a[0], a[1]); w.y = pk2(a[2], a[3]); w.z = pk2(b[0], b[1]); w.w = pk2(b[2], b[3]); return w; }
;     __device__ __forceinline__ void operator()(const f32x4 (&acc)[2][2][4][2], const pg8::Unit& u, int wr, int wc, int fr, int fq) const {
;     ...
;                     const int rowa = 256 * pm + 128 * ai + 64 * wr + 16 * m + tt.rr;
;                     { v4u a, b; if (isq) tt.bf(pack8(o1[0] * QSCALE, o1[1] * QSCALE), pack8(o2[0] * QSCALE, o2[1] * QSCALE), a, b); else tt.bf(pack8(o1[0], o1[1]), pack8(o2[0], o2[1]), a, b);
;                       bf16* d = dst + (size_t)rowa * DA + head * 64 + 8 * tt.p; *(v4u*)d = a; *(v4u*)(d + 8 * DA) = b; }
;                     if (wout) {
;                         const int rl = 128 * ai + 64 * wr + 16 * m + tt.rr;
;                         float* op = sample ? out + OUT_KNEW + (size_t)(rowa - MP) * DA : out + OUT_KWIN + ((size_t)(pm >> 4) * WIN + (256 * (pm & 15) + rl - (SEQ - WIN))) * DA;
;                         op += head * 64 + 4 * tt.p;
;                         f32x4 a, b; tt.f4(o1[0], o1[1], a, b); *(f32x4*)op = a; *(f32x4*)(op + 8 * DA) = b;
;                         tt.f4(o2[0], o2[1], a, b); *(f32x4*)(op + 32) = a; *(f32x4*)(op + 32 + 8 * DA) = b;
.LBB0_516:
	v_cvt_pk_bf16_f32 v54, v54, v55
	v_cvt_pk_bf16_f32 v55, v56, v57
	v_cvt_pk_bf16_f32 v56, v58, v59
	v_cvt_pk_bf16_f32 v57, v60, v61
	ds_write_b128 v166, v[50:53]
	ds_write_b128 v165, v[54:57]
	v_add_u32_e32 v62, 0xa0, v212
	ds_read_b128 v[50:53], v162
	ds_read_b128 v[54:57], v162 offset:1024
	v_ashrrev_i32_e32 v63, 31, v62
	v_lshlrev_b64 v[58:59], 10, v[62:63]
	v_lshl_add_u64 v[58:59], v[214:215], 0, v[58:59]
	s_waitcnt lgkmcnt(1)
	global_store_dwordx4 v[58:59], v[50:53], off
	s_nop 1
	v_add_co_u32_e32 v50, vcc, 0x2000, v58
	s_nop 1
	v_addc_co_u32_e32 v51, vcc, 0, v59, vcc
	s_and_b64 vcc, exec, s[6:7]
	s_waitcnt lgkmcnt(0)
	global_store_dwordx4 v[50:51], v[54:57], off
	s_cbranch_vccnz .LBB0_518
	v_add_u32_e32 v50, 0xffff00a0, v212
	v_add_u32_e32 v51, 0xa0, v199
	s_add_u32 s12, s82, s42
	ds_write_b128 v163, v[22:25]
	ds_write_b128 v164, v[30:33]
	s_addc_u32 s33, s83, s43
	v_cndmask_b32_e64 v50, v51, v50, s[4:5]
	ds_read_b128 v[22:25], v162
	s_and_b64 s[0:1], s[4:5], exec
	v_ashrrev_i32_e32 v51, 31, v50
	s_cselect_b32 s1, s85, s33
	s_cselect_b32 s0, s84, s12
	v_lshlrev_b64 v[30:31], 11, v[50:51]
	v_lshl_add_u64 v[30:31], s[0:1], 0, v[30:31]
	v_lshl_add_u64 v[50:51], v[30:31], 0, v[184:185]
	ds_read_b128 v[30:33], v162 offset:1024
	s_waitcnt lgkmcnt(1)
	global_store_dwordx4 v[50:51], v[22:25], off nt
	ds_write_b128 v163, v[18:21]
	ds_write_b128 v164, v[26:29]
	ds_read_b128 v[18:21], v162
	ds_read_b128 v[22:25], v162 offset:1024
	v_add_co_u32_e32 v52, vcc, 0x4000, v50
	s_nop 1
	v_addc_co_u32_e32 v53, vcc, 0, v51, vcc
	s_waitcnt lgkmcnt(4)
	global_store_dwordx4 v[52:53], v[30:33], off nt
	s_waitcnt lgkmcnt(1)
	global_store_dwordx4 v[50:51], v[18:21], off offset:128 nt
	s_waitcnt lgkmcnt(0)
	global_store_dwordx4 v[52:53], v[22:25], off offset:128 nt

; __device__ __forceinline__ v4u pack8(const f32x4 a, const f32x4 b) { v4u w; w.x = pk2(a[0], a[1]); w.y = pk2(a[2], a[3]); w.z = pk2(b[0], b[1]); w.w = pk2(b[2], b[3]); return w; }
;     __device__ __forceinline__ void operator()(const f32x4 (&acc)[2][2][4][2], const pg8::Unit& u, int wr, int wc, int fr, int fq) const {
;     ...
;                     const int rowa = 256 * pm + 128 * ai + 64 * wr + 16 * m + tt.rr;
;                     { v4u a, b; if (isq) tt.bf(pack8(o1[0] * QSCALE, o1[1] * QSCALE), pack8(o2[0] * QSCALE, o2[1] * QSCALE), a, b); else tt.bf(pack8(o1[0], o1[1]), pack8(o2[0], o2[1]), a, b);
;                       bf16* d = dst + (size_t)rowa * DA + head * 64 + 8 * tt.p; *(v4u*)d = a; *(v4u*)(d + 8 * DA) = b; }
;                     if (wout) {
;                         const int rl = 128 * ai + 64 * wr + 16 * m + tt.rr;
;                         float* op = sample ? out + OUT_KNEW + (size_t)(rowa - MP) * DA : out + OUT_KWIN + ((size_t)(pm >> 4) * WIN + (256 * (pm & 15) + rl - (SEQ - WIN))) * DA;
;                         op += head * 64 + 4 * tt.p;
;                         f32x4 a, b; tt.f4(o1[0], o1[1], a, b); *(f32x4*)op = a; *(f32x4*)(op + 8 * DA) = b;
;                         tt.f4(o2[0], o2[1], a, b); *(f32x4*)(op + 32) = a; *(f32x4*)(op + 32 + 8 * DA) = b;
.LBB0_522:
	v_cvt_pk_bf16_f32 v22, v22, v23
	v_cvt_pk_bf16_f32 v23, v24, v25
	v_cvt_pk_bf16_f32 v24, v26, v27
	v_cvt_pk_bf16_f32 v25, v28, v29
	ds_write_b128 v166, v[18:21]
	ds_write_b128 v165, v[22:25]
	v_add_u32_e32 v30, 0xb0, v212
	ds_read_b128 v[18:21], v162
	ds_read_b128 v[22:25], v162 offset:1024
	v_ashrrev_i32_e32 v31, 31, v30
	v_lshlrev_b64 v[26:27], 10, v[30:31]
	v_lshl_add_u64 v[26:27], v[214:215], 0, v[26:27]
	s_waitcnt lgkmcnt(1)
	global_store_dwordx4 v[26:27], v[18:21], off
	s_nop 1
	v_add_co_u32_e32 v18, vcc, 0x2000, v26
	s_nop 1
	v_addc_co_u32_e32 v19, vcc, 0, v27, vcc
	s_and_b64 vcc, exec, s[6:7]
	s_waitcnt lgkmcnt(0)
	global_store_dwordx4 v[18:19], v[22:25], off
	s_cbranch_vccnz .LBB0_524
	v_add_u32_e32 v18, 0xffff00b0, v212
	v_add_u32_e32 v19, 0xb0, v199
	s_add_u32 s6, s82, s42
	ds_write_b128 v163, v[6:9]
	ds_write_b128 v164, v[14:17]
	s_addc_u32 s7, s83, s43
	v_cndmask_b32_e64 v18, v19, v18, s[4:5]
	ds_read_b128 v[6:9], v162
	s_and_b64 s[0:1], s[4:5], exec
	v_ashrrev_i32_e32 v19, 31, v18
	s_cselect_b32 s1, s85, s7
	s_cselect_b32 s0, s84, s6
	v_lshlrev_b64 v[14:15], 11, v[18:19]
	v_lshl_add_u64 v[14:15], s[0:1], 0, v[14:15]
	v_lshl_add_u64 v[18:19], v[14:15], 0, v[184:185]
	ds_read_b128 v[14:17], v162 offset:1024
	s_waitcnt lgkmcnt(1)
	global_store_dwordx4 v[18:19], v[6:9], off nt
	ds_write_b128 v163, v[2:5]
	ds_write_b128 v164, v[10:13]
	ds_read_b128 v[2:5], v162
	ds_read_b128 v[6:9], v162 offset:1024
	v_add_co_u32_e32 v20, vcc, 0x4000, v18
	s_nop 1
	v_addc_co_u32_e32 v21, vcc, 0, v19, vcc
	s_waitcnt lgkmcnt(4)
	global_store_dwordx4 v[20:21], v[14:17], off nt
	s_waitcnt lgkmcnt(1)
	global_store_dwordx4 v[18:19], v[2:5], off offset:128 nt
	s_waitcnt lgkmcnt(0)
	global_store_dwordx4 v[20:21], v[6:9], off offset:128 nt
